# G1 epilogue q/k loops: loop-invariant qk-norm weight vector loaded once in the preheader instead of every 8-row step
# speedup vs baseline: 1.0194x; 1.0008x over previous
.LBB0_706:
	s_or_saveexec_b64 s[24:25], s[24:25]
	v_lshlrev_b32_e32 v0, 2, v196
	v_readlane_b32 s30, v255, 30
	v_lshrrev_b32_e32 v132, 3, v196
	v_and_b32_e32 v143, 28, v0
	v_and_b32_e32 v0, 7, v200
	v_add_u32_e32 v168, s30, v167
	v_mul_u32_u24_e32 v180, 0x110, v132
	v_lshlrev_b32_e32 v144, 2, v143
	v_or_b32_e32 v169, -8, v132
	v_lshlrev_b32_e32 v182, 4, v0
	v_lshlrev_b32_e32 v138, 3, v0
	v_add_u32_e32 v181, v168, v132
	s_xor_b64 exec, exec, s[24:25]
	s_cbranch_execz .LBB0_722
	v_readlane_b32 s30, v253, 1
	v_cndmask_b32_e64 v0, v217, v218, s[26:27]
	v_readlane_b32 s31, v253, 2
	s_xor_b64 s[26:27], s[26:27], -1
	v_or_b32_e32 v152, 0x80000, v136
	v_lshl_add_u64 v[146:147], s[30:31], 0, v[0:1]
	global_load_dwordx2 v[160:161], v[146:147], off
	v_or_b32_e32 v0, 0xc0000, v150
	v_or_b32_e32 v183, -8, v132
	v_lshlrev_b64 v[132:133], 1, v[134:135]
	s_and_b64 s[30:31], s[28:29], exec
	v_cndmask_b32_e64 v150, v150, v0, s[22:23]
	v_cndmask_b32_e64 v136, v136, v152, s[22:23]
	v_mad_i64_i32 v[132:133], s[22:23], v181, s84, v[132:133]
	s_cselect_b32 s22, 0x80, 64
	v_lshl_add_u64 v[134:135], v[150:151], 1, s[92:93]
	v_cvt_f32_ubyte0_e32 v150, s22
	v_rcp_iflag_f32_e32 v150, v150
	v_cndmask_b32_e64 v153, v220, v221, s[20:21]
	v_cndmask_b32_e64 v0, v153, v222, s[28:29]
	v_sub_u32_e32 v154, 0, v130
	v_mul_f32_e32 v150, 0x4f7ffffe, v150
	v_cvt_u32_f32_e32 v153, v150
	s_cselect_b32 s34, 2, 1
	s_cselect_b32 s35, 7, 6
	v_lshlrev_b32_e32 v0, 2, v0
	s_sub_i32 s23, 0, s22
	v_max_i32_e32 v152, v130, v154
	v_lshl_add_u64 v[154:155], s[12:13], 0, v[0:1]
	v_mul_lo_u32 v0, s23, v153
	v_mul_hi_u32 v0, v153, v0
	v_add_u32_e32 v0, v153, v0
	v_lshl_add_u64 v[132:133], v[130:131], 1, v[132:133]
	v_mul_hi_u32 v0, v152, v0
	v_lshl_add_u64 v[150:151], s[14:15], 0, v[132:133]
	v_mul_lo_u32 v132, v0, s22
	v_sub_u32_e32 v132, v152, v132
	v_add_u32_e32 v133, 1, v0
	v_cmp_le_u32_e32 vcc, s22, v132
	v_readlane_b32 s28, v255, 14
	v_mov_b32_e32 v145, v1
	v_cndmask_b32_e32 v0, v0, v133, vcc
	v_subrev_u32_e32 v133, s22, v132
	v_cndmask_b32_e32 v132, v132, v133, vcc
	v_add_u32_e32 v133, 1, v0
	v_cmp_le_u32_e32 vcc, s22, v132
	v_readlane_b32 s29, v255, 15
	v_add3_u32 v184, v166, v180, v182
	v_cndmask_b32_e32 v0, v0, v133, vcc
	v_xor_b32_e32 v0, v0, v131
	v_sub_u32_e32 v152, v0, v131
	v_mul_lo_u32 v0, v152, s22
	v_sub_u32_e32 v130, v130, v0
	v_ashrrev_i32_e32 v131, 31, v130
	v_lshlrev_b64 v[132:133], 1, v[130:131]
	v_lshl_add_u64 v[130:131], v[130:131], 2, v[154:155]
	v_lshl_add_u64 v[136:137], v[136:137], 1, s[28:29]
	v_lshl_add_u64 v[158:159], v[130:131], 0, v[144:145]
	v_mov_b32_e32 v139, v1
	v_lshlrev_b32_e32 v185, 5, v181
	v_lshl_add_u64 v[146:147], s[78:79], 0, v[144:145]
	v_lshl_add_u64 v[148:149], s[6:7], 0, v[144:145]
	v_ashrrev_i32_e32 v153, 31, v152
	v_lshl_add_u64 v[154:155], v[134:135], 0, v[132:133]
	v_lshl_add_u64 v[156:157], v[136:137], 0, v[132:133]
	s_mov_b64 s[22:23], 0
	s_waitcnt vmcnt(0)
	v_lshl_add_u64 v[130:131], s[90:91], 2, v[160:161]
	v_lshl_add_u64 v[160:161], v[130:131], 0, v[144:145]
	global_load_dwordx4 v[232:235], v[160:161], off
	global_load_dwordx4 v[236:239], v[160:161], off offset:128
	v_and_b32_e32 v0, 0x7fe0, v185
	v_lshlrev_b32_e32 v0, 2, v0
	v_lshl_add_u64 v[250:251], v[146:147], 0, v[0:1]
	global_load_dwordx4 v[242:245], v[250:251], off
	v_lshl_add_u64 v[250:251], v[148:149], 0, v[0:1]
	global_load_dwordx4 v[246:249], v[250:251], off
	global_load_dword v227, v[250:251], off
	global_load_dword v227, v[250:251], off
	s_branch .LBB0_709

.LBB0_709:
	ds_read_b128 v[134:137], v184
	ds_read_b128 v[130:133], v184 offset:128
	s_and_saveexec_b64 s[28:29], s[20:21]
	s_cbranch_execz .LBB0_711
	s_waitcnt lgkmcnt(1)
	v_pk_mul_f32 v[162:163], v[134:135], v[134:135]
	v_pk_mul_f32 v[188:189], v[136:137], v[136:137]
	v_add_f32_e32 v0, v162, v163
	v_add_f32_e32 v0, v0, v188
	s_waitcnt lgkmcnt(0)
	v_pk_mul_f32 v[190:191], v[130:131], v[130:131]
	v_add_f32_e32 v0, v0, v189
	v_add_f32_e32 v0, v0, v190
	v_pk_mul_f32 v[192:193], v[132:133], v[132:133]
	v_add_f32_e32 v0, v0, v191
	v_add_f32_e32 v0, v0, v192
	v_add_f32_e32 v0, v0, v193
	v_cmp_lt_i32_e32 vcc, v214, v208
	s_nop 1
	v_cndmask_b32_e32 v145, v207, v214, vcc
	v_lshlrev_b32_e32 v145, 2, v145
	ds_bpermute_b32 v145, v145, v0
	v_cmp_lt_i32_e32 vcc, v213, v208
	s_waitcnt lgkmcnt(0)
	v_add_f32_e32 v0, v0, v145
	v_cndmask_b32_e32 v145, v207, v213, vcc
	v_lshlrev_b32_e32 v145, 2, v145
	ds_bpermute_b32 v145, v145, v0
	v_cmp_lt_i32_e32 vcc, v212, v208
	s_waitcnt lgkmcnt(0)
	v_add_f32_e32 v0, v0, v145
	v_cndmask_b32_e32 v145, v207, v212, vcc
	v_lshlrev_b32_e32 v145, 2, v145
	ds_bpermute_b32 v145, v145, v0
	s_waitcnt lgkmcnt(0)
	v_add_f32_e32 v0, v0, v145
	v_fmamk_f32 v0, v0, 0x3c800000, v205
	v_cmp_gt_f32_e32 vcc, s33, v0
	v_mul_f32_e32 v145, 0x4b800000, v0
	s_nop 0
	v_cndmask_b32_e32 v0, v0, v145, vcc
	v_rsq_f32_e32 v0, v0
	s_nop 0
	v_mul_f32_e32 v145, 0x45800000, v0
	v_cndmask_b32_e32 v0, v0, v145, vcc
	s_waitcnt vmcnt(4)
	v_pk_mul_f32 v[162:163], v[232:233], v[0:1] op_sel_hi:[1,0]
	s_nop 0
	v_pk_mul_f32 v[134:135], v[134:135], v[162:163]
	s_waitcnt vmcnt(4)
	v_pk_mul_f32 v[162:163], v[236:237], v[0:1] op_sel_hi:[1,0]
	s_nop 0
	v_pk_mul_f32 v[130:131], v[130:131], v[162:163]
	v_pk_mul_f32 v[162:163], v[234:235], v[0:1] op_sel_hi:[1,0]
	s_nop 0
	v_pk_mul_f32 v[136:137], v[136:137], v[162:163]
	v_pk_mul_f32 v[162:163], v[238:239], v[0:1] op_sel_hi:[1,0]
	s_nop 0
	v_pk_mul_f32 v[132:133], v[132:133], v[162:163]
	s_or_b64 exec, exec, s[28:29]
	s_and_saveexec_b64 s[28:29], s[40:41]
	s_cbranch_execz .LBB0_713
	s_branch .LBB0_712

.LBB0_765:
	s_andn2_saveexec_b64 s[22:23], s[22:23]
	s_cbranch_execz .LBB0_781
	v_readlane_b32 s26, v253, 1
	v_cndmask_b32_e64 v0, v217, v218, s[24:25]
	v_readlane_b32 s27, v253, 2
	v_cndmask_b32_e64 v153, 64, v219, s[30:31]
	v_cndmask_b32_e64 v154, v220, v221, s[20:21]
	v_lshl_add_u64 v[132:133], s[26:27], 0, v[0:1]
	global_load_dwordx2 v[132:133], v[132:133], off
	v_or_b32_e32 v0, 0xc0000, v136
	v_cndmask_b32_e64 v136, v136, v0, s[28:29]
	v_cndmask_b32_e64 v0, v154, v222, s[30:31]
	v_cvt_f32_ubyte0_e32 v154, v153
	v_lshlrev_b64 v[134:135], 1, v[134:135]
	v_rcp_iflag_f32_e32 v154, v154
	v_mad_i64_i32 v[134:135], s[26:27], v181, s84, v[134:135]
	v_or_b32_e32 v152, 0x80000, v150
	v_readlane_b32 s26, v255, 14
	v_cndmask_b32_e64 v150, v150, v152, s[28:29]
	v_readlane_b32 s27, v255, 15
	v_sub_u32_e32 v155, 0, v130
	v_sub_u32_e32 v158, 0, v153
	v_lshl_add_u64 v[156:157], v[150:151], 1, s[26:27]
	v_mul_f32_e32 v150, 0x4f7ffffe, v154
	v_cvt_u32_f32_e32 v159, v150
	v_lshlrev_b32_e32 v0, 2, v0
	v_max_i32_e32 v152, v130, v155
	v_lshl_add_u64 v[154:155], s[12:13], 0, v[0:1]
	v_mul_lo_u32 v0, v158, v159
	v_mul_hi_u32 v0, v159, v0
	v_add_u32_e32 v0, v159, v0
	v_lshl_add_u64 v[134:135], v[130:131], 1, v[134:135]
	v_mul_hi_u32 v0, v152, v0
	v_lshl_add_u64 v[150:151], s[14:15], 0, v[134:135]
	v_mul_lo_u32 v134, v0, v153
	v_sub_u32_e32 v134, v152, v134
	v_add_u32_e32 v135, 1, v0
	v_cmp_ge_u32_e32 vcc, v134, v153
	v_mov_b32_e32 v145, v1
	v_lshl_add_u64 v[136:137], v[136:137], 1, s[92:93]
	v_cndmask_b32_e32 v0, v0, v135, vcc
	v_sub_u32_e32 v135, v134, v153
	v_cndmask_b32_e32 v134, v134, v135, vcc
	v_add_u32_e32 v135, 1, v0
	v_cmp_ge_u32_e32 vcc, v134, v153
	s_xor_b64 s[24:25], s[24:25], -1
	v_cndmask_b32_e64 v140, 1, 2, s[30:31]
	v_cndmask_b32_e32 v0, v0, v135, vcc
	v_xor_b32_e32 v0, v0, v131
	v_sub_u32_e32 v152, v0, v131
	v_mul_lo_u32 v0, v152, v153
	v_sub_u32_e32 v130, v130, v0
	v_ashrrev_i32_e32 v131, 31, v130
	v_lshlrev_b64 v[134:135], 1, v[130:131]
	v_lshl_add_u64 v[130:131], v[130:131], 2, v[154:155]
	v_lshl_add_u64 v[158:159], v[130:131], 0, v[144:145]
	v_cndmask_b32_e64 v142, 6, 7, s[30:31]
	v_add3_u32 v141, v166, v180, v182
	v_mov_b32_e32 v139, v1
	v_lshlrev_b32_e32 v162, 5, v181
	v_lshl_add_u64 v[146:147], s[78:79], 0, v[144:145]
	v_lshl_add_u64 v[148:149], s[6:7], 0, v[144:145]
	v_ashrrev_i32_e32 v153, 31, v152
	v_lshl_add_u64 v[154:155], v[136:137], 0, v[134:135]
	v_lshl_add_u64 v[156:157], v[156:157], 0, v[134:135]
	s_mov_b64 s[26:27], 0
	s_waitcnt vmcnt(0)
	v_lshl_add_u64 v[130:131], s[90:91], 2, v[132:133]
	v_lshl_add_u64 v[144:145], v[130:131], 0, v[144:145]
	global_load_dwordx4 v[232:235], v[144:145], off
	global_load_dwordx4 v[236:239], v[144:145], off offset:128
	v_and_b32_e32 v0, 0x7fe0, v162
	v_lshlrev_b32_e32 v0, 2, v0
	v_lshl_add_u64 v[250:251], v[146:147], 0, v[0:1]
	global_load_dwordx4 v[242:245], v[250:251], off
	v_lshl_add_u64 v[250:251], v[148:149], 0, v[0:1]
	global_load_dwordx4 v[246:249], v[250:251], off
	global_load_dword v227, v[250:251], off
	global_load_dword v227, v[250:251], off
	s_branch .LBB0_768

.LBB0_768:
	ds_read_b128 v[134:137], v141
	ds_read_b128 v[130:133], v141 offset:128
	s_and_saveexec_b64 s[28:29], s[20:21]
	s_cbranch_execz .LBB0_770
	s_waitcnt lgkmcnt(1)
	v_pk_mul_f32 v[160:161], v[134:135], v[134:135]
	v_pk_mul_f32 v[166:167], v[136:137], v[136:137]
	v_add_f32_e32 v0, v160, v161
	v_add_f32_e32 v0, v0, v166
	s_waitcnt lgkmcnt(0)
	v_pk_mul_f32 v[170:171], v[130:131], v[130:131]
	v_add_f32_e32 v0, v0, v167
	v_add_f32_e32 v0, v0, v170
	v_pk_mul_f32 v[172:173], v[132:133], v[132:133]
	v_add_f32_e32 v0, v0, v171
	v_add_f32_e32 v0, v0, v172
	v_add_f32_e32 v0, v0, v173
	v_cmp_lt_i32_e32 vcc, v214, v208
	s_nop 1
	v_cndmask_b32_e32 v160, v207, v214, vcc
	v_lshlrev_b32_e32 v160, 2, v160
	ds_bpermute_b32 v160, v160, v0
	v_cmp_lt_i32_e32 vcc, v213, v208
	s_waitcnt lgkmcnt(0)
	v_add_f32_e32 v0, v0, v160
	v_cndmask_b32_e32 v160, v207, v213, vcc
	v_lshlrev_b32_e32 v160, 2, v160
	ds_bpermute_b32 v160, v160, v0
	v_cmp_lt_i32_e32 vcc, v212, v208
	s_waitcnt lgkmcnt(0)
	v_add_f32_e32 v0, v0, v160
	v_cndmask_b32_e32 v160, v207, v212, vcc
	v_lshlrev_b32_e32 v160, 2, v160
	ds_bpermute_b32 v160, v160, v0
	s_waitcnt lgkmcnt(0)
	v_add_f32_e32 v0, v0, v160
	v_fmamk_f32 v0, v0, 0x3c800000, v205
	v_cmp_gt_f32_e32 vcc, s33, v0
	v_mul_f32_e32 v160, 0x4b800000, v0
	s_nop 0
	v_cndmask_b32_e32 v0, v0, v160, vcc
	v_rsq_f32_e32 v0, v0
	s_nop 0
	v_mul_f32_e32 v160, 0x45800000, v0
	v_cndmask_b32_e32 v0, v0, v160, vcc
	s_waitcnt vmcnt(4)
	v_pk_mul_f32 v[160:161], v[232:233], v[0:1] op_sel_hi:[1,0]
	s_nop 0
	v_pk_mul_f32 v[134:135], v[134:135], v[160:161]
	s_waitcnt vmcnt(4)
	v_pk_mul_f32 v[160:161], v[236:237], v[0:1] op_sel_hi:[1,0]
	s_nop 0
	v_pk_mul_f32 v[130:131], v[130:131], v[160:161]
	v_pk_mul_f32 v[160:161], v[234:235], v[0:1] op_sel_hi:[1,0]
	s_nop 0
	v_pk_mul_f32 v[136:137], v[136:137], v[160:161]
	v_pk_mul_f32 v[160:161], v[238:239], v[0:1] op_sel_hi:[1,0]
	s_nop 0
	v_pk_mul_f32 v[132:133], v[132:133], v[160:161]
	s_or_b64 exec, exec, s[28:29]
	s_and_saveexec_b64 s[28:29], s[40:41]
	s_cbranch_execz .LBB0_772
	s_branch .LBB0_771
